# differential attention: wave-uniform mask test without cndmask/readfirstlane/bitcmp chain (7.12-style trim), otherwise identical to the best version
# baseline (speedup 1.0000x reference)
; template <int TYPE>
; DI void attn_item(const Params& p, int layer, int head, int qt, int dil, int res, int chunk, char* smem) {
;     ...
;     __syncthreads();
;     if (TYPE == 2) {
;       if ((sflag[0] & sflag[1] & sflag[2] & sflag[3] & sflag[4] & sflag[5] & sflag[6] & sflag[7]) != 0) break;
;     }
;     *(uint4*)(sK + swz(kkey0, kchunk)) = kreg0;
;     ...
;     ATT_VSTORE(vreg0, vdc0)
;     __syncthreads();
;     ATT_PREFETCH((kt > kt_lo) ? kt - 1 : kt);
;     ...
;       const int Ks = Kb + 32 * sub;
;       bool need;
;       if (TYPE == 0) need = (Ks <= wq0 + 31) && (Ks + 31 >= wq0 - 128);
;       else if (TYPE == 1) need = (Ks <= wq0 + 31);
;       else need = (Ks < wq0 + 31) && (sflag[wid] == 0);
;       if (!need) continue;
;       const int db = Uq - Ks - 4 * h;
;       f32x16 s1, s2;
;       if (TYPE == 2) {
; #pragma unroll
;         for (int i = 0; i < 16; ++i) { s1[i] = 0.f; s2[i] = 0.f; }
;       } else {
;         const float base = -slope * (float)db - cref;
;         const bool msk = (TYPE == 0) ? true : (__builtin_amdgcn_readfirstlane((Ks + 31 > wq0) ? 1 : 0) != 0);
;         if (msk) {
; #pragma unroll
;           for (int i = 0; i < 16; ++i) {
;             const int ci = (i & 3) + 8 * (i >> 2);
;             const int dist = db - ci;
;             s1[i] = (dist >= 0 && dist <= wlim) ? fmaf(slope, (float)ci, base) : -1e30f;
;             s2[i] = s1[i];
;           }
;         } else {
; #pragma unroll
;           for (int i = 0; i < 16; ++i) {
;             const int ci = (i & 3) + 8 * (i >> 2);
;             s1[i] = fmaf(slope, (float)ci, base);
;             s2[i] = s1[i];
.LBB0_202:
	v_cmp_gt_i32_e32 vcc, v133, v152
	s_barrier
	s_nop 0
	v_subbrev_co_u32_e32 v0, vcc, 0, v133, vcc
	v_lshlrev_b32_e32 v0, 6, v0
	v_add_u32_e32 v66, v0, v137
	v_or_b32_e32 v0, v0, v177
	v_mad_i64_i32 v[66:67], s[4:5], v66, s85, v[154:155]
	s_waitcnt vmcnt(0)
	ds_write_b128 v186, v[118:121]
	ds_write_b16 v187, v114 offset:8192
	ds_write_b16_d16_hi v187, v114 offset:8320
	ds_write_b16 v188, v115 offset:8192
	ds_write_b16_d16_hi v189, v115 offset:8192
	ds_write_b16 v190, v116 offset:8192
	ds_write_b16_d16_hi v191, v116 offset:8192
	ds_write_b16 v192, v117 offset:8192
	ds_write_b16_d16_hi v193, v117 offset:8192
	s_waitcnt lgkmcnt(0)
	s_barrier
	v_mad_i64_i32 v[68:69], s[4:5], v0, s85, v[156:157]
	global_load_dwordx4 v[118:121], v[66:67], off
	global_load_dwordx4 v[114:117], v[68:69], off
	v_cmp_le_i32_e64 s[4:5], v133, v152
	v_add_u32_e32 v0, 32, v139
	v_cmp_le_i32_e32 vcc, v0, v141
	s_and_saveexec_b64 s[76:77], vcc
	s_cbranch_execz .LBB0_208
	v_subrev_u32_e32 v82, 32, v185
	v_add_u32_e32 v66, 63, v139
	v_cvt_f32_i32_e32 v0, v82
	v_cmp_gt_i32_e32 vcc, v66, v176
	s_mov_b64 s[78:79], -1
	v_fma_f32 v0, -v146, v0, -v135
	v_add_f32_e32 v67, v146, v0
	s_cmp_lg_u64 vcc, 0
	s_cselect_b64 s[96:97], -1, 0
	s_and_b64 vcc, exec, s[96:97]
	v_fma_f32 v66, 0, v146, v0
	s_cbranch_vccnz .LBB0_205
	v_pk_fma_f32 v[68:69], v[146:147], s[54:55], v[0:1] op_sel_hi:[1,1,0]
	v_pk_fma_f32 v[70:71], v[146:147], s[56:57], v[0:1] op_sel_hi:[1,1,0]
	v_pk_fma_f32 v[72:73], v[146:147], s[58:59], v[0:1] op_sel_hi:[1,1,0]
	v_pk_fma_f32 v[74:75], v[146:147], s[60:61], v[0:1] op_sel_hi:[1,1,0]
	v_pk_fma_f32 v[76:77], v[146:147], s[62:63], v[0:1] op_sel_hi:[1,1,0]
	v_pk_fma_f32 v[78:79], v[146:147], s[52:53], v[0:1] op_sel_hi:[1,1,0]
	v_pk_fma_f32 v[80:81], v[146:147], s[64:65], v[0:1] op_sel_hi:[1,1,0]
	s_mov_b64 s[78:79], 0

; template <int TYPE>
; DI void attn_item(const Params& p, int layer, int head, int qt, int dil, int res, int chunk, char* smem) {
;     ...
;       const int Ks = Kb + 32 * sub;
;       bool need;
;       if (TYPE == 0) need = (Ks <= wq0 + 31) && (Ks + 31 >= wq0 - 128);
;       else if (TYPE == 1) need = (Ks <= wq0 + 31);
;       else need = (Ks < wq0 + 31) && (sflag[wid] == 0);
;       if (!need) continue;
;       const int db = Uq - Ks - 4 * h;
;       f32x16 s1, s2;
;       if (TYPE == 2) {
; #pragma unroll
;         for (int i = 0; i < 16; ++i) { s1[i] = 0.f; s2[i] = 0.f; }
;       } else {
;         const float base = -slope * (float)db - cref;
;         const bool msk = (TYPE == 0) ? true : (__builtin_amdgcn_readfirstlane((Ks + 31 > wq0) ? 1 : 0) != 0);
;         if (msk) {
; #pragma unroll
;           for (int i = 0; i < 16; ++i) {
;             const int ci = (i & 3) + 8 * (i >> 2);
;             const int dist = db - ci;
;             s1[i] = (dist >= 0 && dist <= wlim) ? fmaf(slope, (float)ci, base) : -1e30f;
;             s2[i] = s1[i];
;           }
;         } else {
; #pragma unroll
;           for (int i = 0; i < 16; ++i) {
;             const int ci = (i & 3) + 8 * (i >> 2);
;             s1[i] = fmaf(slope, (float)ci, base);
;             s2[i] = s1[i];
.LBB0_208:
	s_or_b64 exec, exec, s[76:77]
	s_and_b64 s[4:5], exec, s[4:5]
	s_or_b64 s[74:75], s[4:5], s[74:75]
	v_cmp_le_i32_e32 vcc, v139, v141
	s_and_saveexec_b64 s[4:5], vcc
	s_cbranch_execz .LBB0_201
	v_add_u32_e32 v66, 31, v139
	v_cvt_f32_i32_e32 v0, v185
	v_cmp_gt_i32_e32 vcc, v66, v176
	s_mov_b64 s[76:77], -1
	v_fma_f32 v0, -v146, v0, -v135
	v_add_f32_e32 v67, v146, v0
	s_cmp_lg_u64 vcc, 0
	s_cselect_b64 s[78:79], -1, 0
	s_and_b64 vcc, exec, s[78:79]
	v_fma_f32 v66, 0, v146, v0
	s_cbranch_vccnz .LBB0_211
	v_pk_fma_f32 v[68:69], v[146:147], s[54:55], v[0:1] op_sel_hi:[1,1,0]
	v_pk_fma_f32 v[70:71], v[146:147], s[56:57], v[0:1] op_sel_hi:[1,1,0]
	v_pk_fma_f32 v[72:73], v[146:147], s[58:59], v[0:1] op_sel_hi:[1,1,0]
	v_pk_fma_f32 v[74:75], v[146:147], s[60:61], v[0:1] op_sel_hi:[1,1,0]
	v_pk_fma_f32 v[76:77], v[146:147], s[62:63], v[0:1] op_sel_hi:[1,1,0]
	v_pk_fma_f32 v[78:79], v[146:147], s[52:53], v[0:1] op_sel_hi:[1,1,0]
	v_pk_fma_f32 v[80:81], v[146:147], s[64:65], v[0:1] op_sel_hi:[1,1,0]
	s_mov_b64 s[76:77], 0

; template <int TYPE>
; DI void attn_item(const Params& p, int layer, int head, int qt, int dil, int res, int chunk, char* smem) {
;     ...
;     __syncthreads();
;     if (TYPE == 2) {
;       if ((sflag[0] & sflag[1] & sflag[2] & sflag[3] & sflag[4] & sflag[5] & sflag[6] & sflag[7]) != 0) break;
;     }
;     *(uint4*)(sK + swz(kkey0, kchunk)) = kreg0;
;     ...
;     ATT_VSTORE(vreg0, vdc0)
;     __syncthreads();
;     ATT_PREFETCH((kt > kt_lo) ? kt - 1 : kt);
;     ...
;       const int Ks = Kb + 32 * sub;
;       bool need;
;       if (TYPE == 0) need = (Ks <= wq0 + 31) && (Ks + 31 >= wq0 - 128);
;       else if (TYPE == 1) need = (Ks <= wq0 + 31);
;       else need = (Ks < wq0 + 31) && (sflag[wid] == 0);
;       if (!need) continue;
;       const int db = Uq - Ks - 4 * h;
;       f32x16 s1, s2;
;       if (TYPE == 2) {
; #pragma unroll
;         for (int i = 0; i < 16; ++i) { s1[i] = 0.f; s2[i] = 0.f; }
;       } else {
;         const float base = -slope * (float)db - cref;
;         const bool msk = (TYPE == 0) ? true : (__builtin_amdgcn_readfirstlane((Ks + 31 > wq0) ? 1 : 0) != 0);
;         if (msk) {
; #pragma unroll
;           for (int i = 0; i < 16; ++i) {
;             const int ci = (i & 3) + 8 * (i >> 2);
;             const int dist = db - ci;
;             s1[i] = (dist >= 0 && dist <= wlim) ? fmaf(slope, (float)ci, base) : -1e30f;
;             s2[i] = s1[i];
;           }
;         } else {
; #pragma unroll
;           for (int i = 0; i < 16; ++i) {
;             const int ci = (i & 3) + 8 * (i >> 2);
;             s1[i] = fmaf(slope, (float)ci, base);
;             s2[i] = s1[i];
.LBB0_578:
	v_cmp_gt_i32_e32 vcc, v133, v152
	s_barrier
	s_nop 0
	v_subbrev_co_u32_e32 v0, vcc, 0, v133, vcc
	v_lshlrev_b32_e32 v0, 6, v0
	v_add_u32_e32 v66, v0, v137
	v_or_b32_e32 v0, v0, v145
	v_mad_i64_i32 v[66:67], s[4:5], v66, s79, v[154:155]
	s_waitcnt vmcnt(0)
	ds_write_b128 v178, v[118:121]
	ds_write_b16 v179, v114 offset:8192
	ds_write_b16_d16_hi v179, v114 offset:8320
	ds_write_b16 v180, v115 offset:8192
	ds_write_b16_d16_hi v181, v115 offset:8192
	ds_write_b16 v182, v116 offset:8192
	ds_write_b16_d16_hi v183, v116 offset:8192
	ds_write_b16 v184, v117 offset:8192
	ds_write_b16_d16_hi v185, v117 offset:8192
	s_waitcnt lgkmcnt(0)
	s_barrier
	v_mad_i64_i32 v[68:69], s[4:5], v0, s79, v[156:157]
	global_load_dwordx4 v[118:121], v[66:67], off
	global_load_dwordx4 v[114:117], v[68:69], off
	v_cmp_le_i32_e64 s[4:5], v133, v152
	v_add_u32_e32 v0, 32, v139
	v_cmp_le_i32_e32 vcc, v0, v141
	s_and_saveexec_b64 s[68:69], vcc
	s_cbranch_execz .LBB0_584
	v_subrev_u32_e32 v82, 32, v177
	v_add_u32_e32 v66, 63, v139
	v_cvt_f32_i32_e32 v0, v82
	v_cmp_gt_i32_e32 vcc, v66, v174
	s_mov_b64 s[70:71], -1
	v_fma_f32 v0, -v146, v0, -v135
	v_add_f32_e32 v67, v146, v0
	s_cmp_lg_u64 vcc, 0
	s_cselect_b64 s[90:91], -1, 0
	s_and_b64 vcc, exec, s[90:91]
	v_fma_f32 v66, 0, v146, v0
	s_cbranch_vccnz .LBB0_581
	v_pk_fma_f32 v[68:69], v[146:147], s[44:45], v[0:1] op_sel_hi:[1,1,0]
	v_pk_fma_f32 v[70:71], v[146:147], s[46:47], v[0:1] op_sel_hi:[1,1,0]
	v_pk_fma_f32 v[72:73], v[146:147], s[48:49], v[0:1] op_sel_hi:[1,1,0]
	v_pk_fma_f32 v[74:75], v[146:147], s[52:53], v[0:1] op_sel_hi:[1,1,0]
	v_pk_fma_f32 v[76:77], v[146:147], s[54:55], v[0:1] op_sel_hi:[1,1,0]
	v_pk_fma_f32 v[78:79], v[146:147], s[42:43], v[0:1] op_sel_hi:[1,1,0]
	v_pk_fma_f32 v[80:81], v[146:147], s[56:57], v[0:1] op_sel_hi:[1,1,0]
	s_mov_b64 s[70:71], 0

; template <int TYPE>
; DI void attn_item(const Params& p, int layer, int head, int qt, int dil, int res, int chunk, char* smem) {
;     ...
;       const int Ks = Kb + 32 * sub;
;       bool need;
;       if (TYPE == 0) need = (Ks <= wq0 + 31) && (Ks + 31 >= wq0 - 128);
;       else if (TYPE == 1) need = (Ks <= wq0 + 31);
;       else need = (Ks < wq0 + 31) && (sflag[wid] == 0);
;       if (!need) continue;
;       const int db = Uq - Ks - 4 * h;
;       f32x16 s1, s2;
;       if (TYPE == 2) {
; #pragma unroll
;         for (int i = 0; i < 16; ++i) { s1[i] = 0.f; s2[i] = 0.f; }
;       } else {
;         const float base = -slope * (float)db - cref;
;         const bool msk = (TYPE == 0) ? true : (__builtin_amdgcn_readfirstlane((Ks + 31 > wq0) ? 1 : 0) != 0);
;         if (msk) {
; #pragma unroll
;           for (int i = 0; i < 16; ++i) {
;             const int ci = (i & 3) + 8 * (i >> 2);
;             const int dist = db - ci;
;             s1[i] = (dist >= 0 && dist <= wlim) ? fmaf(slope, (float)ci, base) : -1e30f;
;             s2[i] = s1[i];
;           }
;         } else {
; #pragma unroll
;           for (int i = 0; i < 16; ++i) {
;             const int ci = (i & 3) + 8 * (i >> 2);
;             s1[i] = fmaf(slope, (float)ci, base);
;             s2[i] = s1[i];
.LBB0_584:
	s_or_b64 exec, exec, s[68:69]
	s_and_b64 s[4:5], exec, s[4:5]
	s_or_b64 s[66:67], s[4:5], s[66:67]
	v_cmp_le_i32_e32 vcc, v139, v141
	s_and_saveexec_b64 s[4:5], vcc
	s_cbranch_execz .LBB0_577
	v_add_u32_e32 v66, 31, v139
	v_cvt_f32_i32_e32 v0, v177
	v_cmp_gt_i32_e32 vcc, v66, v174
	s_mov_b64 s[68:69], -1
	v_fma_f32 v0, -v146, v0, -v135
	v_add_f32_e32 v67, v146, v0
	s_cmp_lg_u64 vcc, 0
	s_cselect_b64 s[70:71], -1, 0
	s_and_b64 vcc, exec, s[70:71]
	v_fma_f32 v66, 0, v146, v0
	s_cbranch_vccnz .LBB0_587
	v_pk_fma_f32 v[68:69], v[146:147], s[44:45], v[0:1] op_sel_hi:[1,1,0]
	v_pk_fma_f32 v[70:71], v[146:147], s[46:47], v[0:1] op_sel_hi:[1,1,0]
	v_pk_fma_f32 v[72:73], v[146:147], s[48:49], v[0:1] op_sel_hi:[1,1,0]
	v_pk_fma_f32 v[74:75], v[146:147], s[52:53], v[0:1] op_sel_hi:[1,1,0]
	v_pk_fma_f32 v[76:77], v[146:147], s[54:55], v[0:1] op_sel_hi:[1,1,0]
	v_pk_fma_f32 v[78:79], v[146:147], s[42:43], v[0:1] op_sel_hi:[1,1,0]
	v_pk_fma_f32 v[80:81], v[146:147], s[56:57], v[0:1] op_sel_hi:[1,1,0]
	s_mov_b64 s[68:69], 0
